# combined: extended back-edge rotation + K norms from the proj1 epilogue + Cauchy-Schwarz early exit
# speedup vs baseline: 1.0026x; 1.0026x over previous
.Lff1a_top2:
	s_waitcnt vmcnt(3)
	ds_write_b128 v250, v[130:133]
	s_waitcnt vmcnt(2)
	ds_write_b128 v251, v[134:137] offset:34816
	s_waitcnt vmcnt(1)
	ds_write_b128 v252, v[138:141]
	s_waitcnt vmcnt(0)
	ds_write_b128 v253, v[142:145] offset:34816
	global_load_dwordx4 v[130:133], v150, s[80:81]
	global_load_dwordx4 v[134:137], v150, s[82:83]
	global_load_dwordx4 v[138:141], v152, s[80:81]
	global_load_dwordx4 v[142:145], v152, s[82:83]
	s_waitcnt lgkmcnt(4)
	v_readfirstlane_b32 s86, v153
	s_cmpk_eq_u32 s86, 0x200
	s_cbranch_scc1 .Lff1a_exit
	s_cmp_gt_i32 s77, s74
	s_cbranch_scc1 .Lff1a_inact
	s_cmp_eq_u32 s72, 0
	s_cbranch_scc1 .Lff1a_first
	s_mul_i32 s34, s27, 0x4400
	v_add_u32_e32 v0, s34, v162
	ds_read_b128 v[198:201], v0
	ds_read_b128 v[202:205], v0 offset:32
	ds_read_b128 v[206:209], v0 offset:8704
	ds_read_b128 v[210:213], v0 offset:8736
	v_add_u32_e32 v246, s75, v149
	v_add_u32_e32 v234, 0x12800, v246
	v_add_u32_e32 v235, 0x12880, v246
	v_add_u32_e32 v238, 0x12820, v246
	v_add_u32_e32 v239, 0x128a0, v246
	v_add_u32_e32 v242, 0x12840, v246
	v_add_u32_e32 v243, 0x128c0, v246
	v_add_u32_e32 v247, 0x12860, v246
	v_add_u32_e32 v246, 0x128e0, v246
	ds_read_b128 v[218:221], v234
	ds_read_b128 v[234:237], v235
	ds_read_b128 v[222:225], v238
	ds_read_b128 v[238:241], v239
	ds_read_b128 v[226:229], v242
	ds_read_b128 v[242:245], v243
	ds_read_b128 v[230:233], v247
	ds_read_b128 v[246:249], v246
	s_waitcnt lgkmcnt(1)
	v_mfma_f32_32x32x16_bf16 v[218:233], v[198:201], v[98:101], v[218:233]
	v_sub_f32_e32 v82, v82, v197
	v_sub_f32_e32 v83, v83, v197
	v_sub_f32_e32 v84, v84, v197
	v_sub_f32_e32 v85, v85, v197
	v_exp_f32_e32 v82, v82
	v_exp_f32_e32 v83, v83
	v_exp_f32_e32 v84, v84
	v_exp_f32_e32 v85, v85
	s_waitcnt lgkmcnt(0)
	v_mfma_f32_32x32x16_bf16 v[234:249], v[206:209], v[98:101], v[234:249]
	v_sub_f32_e32 v86, v86, v197
	v_sub_f32_e32 v87, v87, v197
	v_sub_f32_e32 v88, v88, v197
	v_sub_f32_e32 v89, v89, v197
	v_exp_f32_e32 v86, v86
	v_exp_f32_e32 v87, v87
	v_exp_f32_e32 v88, v88
	v_exp_f32_e32 v89, v89
	v_mfma_f32_32x32x16_bf16 v[218:233], v[202:205], v[102:105], v[218:233]
	v_sub_f32_e32 v66, v66, v197
	v_sub_f32_e32 v67, v67, v197
	v_sub_f32_e32 v68, v68, v197
	v_sub_f32_e32 v69, v69, v197
	v_exp_f32_e32 v66, v66
	v_exp_f32_e32 v67, v67
	v_exp_f32_e32 v68, v68
	v_exp_f32_e32 v69, v69
	ds_read_b128 v[198:201], v0 offset:64
	ds_read_b128 v[202:205], v0 offset:96
	ds_read_b128 v[206:209], v0 offset:8768
	ds_read_b128 v[214:217], v0 offset:8800
	v_mfma_f32_32x32x16_bf16 v[234:249], v[210:213], v[102:105], v[234:249]
	v_add_f32_e32 v250, v82, v86
	v_add_f32_e32 v251, v83, v87
	v_add_f32_e32 v252, v84, v88
	v_add_f32_e32 v253, v85, v89
	v_sub_f32_e32 v70, v70, v197
	v_sub_f32_e32 v71, v71, v197
	v_sub_f32_e32 v72, v72, v197
	v_sub_f32_e32 v73, v73, v197
	s_waitcnt lgkmcnt(3)
	v_mfma_f32_32x32x16_bf16 v[218:233], v[198:201], v[106:109], v[218:233]
	v_exp_f32_e32 v70, v70
	v_exp_f32_e32 v71, v71
	v_exp_f32_e32 v72, v72
	v_exp_f32_e32 v73, v73
	v_add_f32_e32 v250, v250, v66
	v_add_f32_e32 v251, v251, v67
	v_add_f32_e32 v252, v252, v68
	v_add_f32_e32 v253, v253, v69
	s_waitcnt lgkmcnt(1)
	v_mfma_f32_32x32x16_bf16 v[234:249], v[206:209], v[106:109], v[234:249]
	v_sub_f32_e32 v90, v90, v197
	v_sub_f32_e32 v91, v91, v197
	v_sub_f32_e32 v92, v92, v197
	v_sub_f32_e32 v93, v93, v197
	v_exp_f32_e32 v90, v90
	v_exp_f32_e32 v91, v91
	v_exp_f32_e32 v92, v92
	v_exp_f32_e32 v93, v93
	v_mfma_f32_32x32x16_bf16 v[218:233], v[202:205], v[110:113], v[218:233]
	v_add_f32_e32 v250, v250, v70
	v_add_f32_e32 v251, v251, v71
	v_add_f32_e32 v252, v252, v72
	v_add_f32_e32 v253, v253, v73
	v_sub_f32_e32 v94, v94, v197
	v_sub_f32_e32 v95, v95, v197
	v_sub_f32_e32 v96, v96, v197
	v_sub_f32_e32 v97, v97, v197
	ds_read_b128 v[198:201], v0 offset:128
	ds_read_b128 v[202:205], v0 offset:160
	ds_read_b128 v[206:209], v0 offset:8832
	ds_read_b128 v[210:213], v0 offset:8864
	s_waitcnt lgkmcnt(4)
	v_mfma_f32_32x32x16_bf16 v[234:249], v[214:217], v[110:113], v[234:249]
	v_exp_f32_e32 v94, v94
	v_exp_f32_e32 v95, v95
	v_exp_f32_e32 v96, v96
	v_exp_f32_e32 v97, v97
	v_add_f32_e32 v250, v250, v90
	v_add_f32_e32 v251, v251, v91
	v_add_f32_e32 v252, v252, v92
	v_add_f32_e32 v253, v253, v93
	s_waitcnt lgkmcnt(3)
	v_mfma_f32_32x32x16_bf16 v[218:233], v[198:201], v[114:117], v[218:233]
	v_sub_f32_e32 v74, v74, v197
	v_sub_f32_e32 v75, v75, v197
	v_sub_f32_e32 v76, v76, v197
	v_sub_f32_e32 v77, v77, v197
	v_exp_f32_e32 v74, v74
	v_exp_f32_e32 v75, v75
	v_exp_f32_e32 v76, v76
	v_exp_f32_e32 v77, v77
	s_waitcnt lgkmcnt(1)
	v_mfma_f32_32x32x16_bf16 v[234:249], v[206:209], v[114:117], v[234:249]
	v_add_f32_e32 v250, v250, v94
	v_add_f32_e32 v251, v251, v95
	v_add_f32_e32 v252, v252, v96
	v_add_f32_e32 v253, v253, v97
	v_sub_f32_e32 v78, v78, v197
	v_sub_f32_e32 v79, v79, v197
	v_sub_f32_e32 v80, v80, v197
	v_sub_f32_e32 v81, v81, v197
	v_mfma_f32_32x32x16_bf16 v[218:233], v[202:205], v[118:121], v[218:233]
	v_exp_f32_e32 v78, v78
	v_exp_f32_e32 v79, v79
	v_exp_f32_e32 v80, v80
	v_exp_f32_e32 v81, v81
	v_add_f32_e32 v250, v250, v74
	v_add_f32_e32 v251, v251, v75
	v_add_f32_e32 v252, v252, v76
	v_add_f32_e32 v253, v253, v77
	ds_read_b128 v[198:201], v0 offset:192
	ds_read_b128 v[202:205], v0 offset:224
	ds_read_b128 v[206:209], v0 offset:8896
	ds_read_b128 v[214:217], v0 offset:8928
	s_waitcnt lgkmcnt(4)
	v_mfma_f32_32x32x16_bf16 v[234:249], v[210:213], v[118:121], v[234:249]
	v_add_f32_e32 v250, v250, v78
	v_add_f32_e32 v251, v251, v79
	v_add_f32_e32 v252, v252, v80
	v_add_f32_e32 v253, v253, v81
	v_add_f32_e32 v250, v250, v251
	v_add_f32_e32 v252, v252, v253
	v_add_f32_e32 v250, v250, v252
	v_add_f32_e32 v196, v196, v250
	s_waitcnt lgkmcnt(3)
	v_mfma_f32_32x32x16_bf16 v[218:233], v[198:201], v[122:125], v[218:233]
	v_cvt_pk_bf16_f32 v73, v72, v73
	v_cvt_pk_bf16_f32 v72, v70, v71
	v_cvt_pk_bf16_f32 v71, v68, v69
	v_cvt_pk_bf16_f32 v70, v66, v67
	v_cvt_pk_bf16_f32 v66, v82, v83
	v_cvt_pk_bf16_f32 v67, v84, v85
	v_cvt_pk_bf16_f32 v68, v86, v87
	v_cvt_pk_bf16_f32 v69, v88, v89
	s_waitcnt lgkmcnt(1)
	v_mfma_f32_32x32x16_bf16 v[234:249], v[206:209], v[122:125], v[234:249]
	v_cvt_pk_bf16_f32 v81, v80, v81
	v_cvt_pk_bf16_f32 v80, v78, v79
	v_cvt_pk_bf16_f32 v79, v76, v77
	v_cvt_pk_bf16_f32 v78, v74, v75
	v_cvt_pk_bf16_f32 v74, v90, v91
	v_cvt_pk_bf16_f32 v75, v92, v93
	v_cvt_pk_bf16_f32 v76, v94, v95
	v_cvt_pk_bf16_f32 v77, v96, v97
	v_mfma_f32_32x32x16_bf16 v[218:233], v[202:205], v[126:129], v[218:233]
	s_waitcnt lgkmcnt(0)
	v_mfma_f32_32x32x16_bf16 v[234:249], v[214:217], v[126:129], v[234:249]
	s_add_i32 s76, s77, 63
	s_cmp_le_i32 s76, s5
	s_cbranch_scc1 .Lff1a_z2
	v_cmp_le_i32_e32 vcc, v165, v195
	s_nop 8
	v_cndmask_b32_e32 v234, v155, v234, vcc
	v_cmp_lt_i32_e32 vcc, v163, v195
	s_nop 1
	v_cndmask_b32_e32 v219, v155, v219, vcc
	v_cmp_le_i32_e32 vcc, v163, v195
	s_nop 1
	v_cndmask_b32_e32 v218, v155, v218, vcc
	v_cmp_le_i32_e32 vcc, v166, v195
	s_nop 1
	v_cndmask_b32_e32 v235, v155, v235, vcc
	v_cmp_le_i32_e32 vcc, v167, v195
	s_nop 1
	v_cndmask_b32_e32 v220, v155, v220, vcc
	v_cmp_le_i32_e32 vcc, v168, v195
	s_nop 1
	v_cndmask_b32_e32 v236, v155, v236, vcc
	v_cmp_le_i32_e32 vcc, v169, v195
	s_nop 1
	v_cndmask_b32_e32 v221, v155, v221, vcc
	v_cmp_le_i32_e32 vcc, v170, v195
	s_nop 1
	v_cndmask_b32_e32 v237, v155, v237, vcc
	v_cmp_le_i32_e32 vcc, v171, v195
	s_nop 1
	v_cndmask_b32_e32 v222, v155, v222, vcc
	v_cmp_le_i32_e32 vcc, v172, v195
	s_nop 1
	v_cndmask_b32_e32 v238, v155, v238, vcc
	v_cmp_le_i32_e32 vcc, v173, v195
	s_nop 1
	v_cndmask_b32_e32 v223, v155, v223, vcc
	v_cmp_le_i32_e32 vcc, v174, v195
	s_nop 1
	v_cndmask_b32_e32 v239, v155, v239, vcc
	v_cmp_le_i32_e32 vcc, v175, v195
	s_nop 1
	v_cndmask_b32_e32 v224, v155, v224, vcc
	v_cmp_le_i32_e32 vcc, v176, v195
	s_nop 1
	v_cndmask_b32_e32 v240, v155, v240, vcc
	v_cmp_le_i32_e32 vcc, v177, v195
	s_nop 1
	v_cndmask_b32_e32 v225, v155, v225, vcc
	v_cmp_le_i32_e32 vcc, v178, v195
	s_nop 1
	v_cndmask_b32_e32 v241, v155, v241, vcc
	v_cmp_le_i32_e32 vcc, v179, v195
	s_nop 1
	v_cndmask_b32_e32 v226, v155, v226, vcc
	v_cmp_le_i32_e32 vcc, v180, v195
	s_nop 1
	v_cndmask_b32_e32 v242, v155, v242, vcc
	v_cmp_le_i32_e32 vcc, v181, v195
	s_nop 1
	v_cndmask_b32_e32 v227, v155, v227, vcc
	v_cmp_le_i32_e32 vcc, v182, v195
	s_nop 1
	v_cndmask_b32_e32 v243, v155, v243, vcc
	v_cmp_le_i32_e32 vcc, v183, v195
	s_nop 1
	v_cndmask_b32_e32 v228, v155, v228, vcc
	v_cmp_le_i32_e32 vcc, v184, v195
	s_nop 1
	v_cndmask_b32_e32 v244, v155, v244, vcc
	v_cmp_le_i32_e32 vcc, v185, v195
	s_nop 1
	v_cndmask_b32_e32 v229, v155, v229, vcc
	v_cmp_le_i32_e32 vcc, v186, v195
	s_nop 1
	v_cndmask_b32_e32 v245, v155, v245, vcc
	v_cmp_le_i32_e32 vcc, v187, v195
	s_nop 1
	v_cndmask_b32_e32 v230, v155, v230, vcc
	v_cmp_le_i32_e32 vcc, v188, v195
	s_nop 1
	v_cndmask_b32_e32 v246, v155, v246, vcc
	v_cmp_le_i32_e32 vcc, v189, v195
	s_nop 1
	v_cndmask_b32_e32 v231, v155, v231, vcc
	v_cmp_le_i32_e32 vcc, v190, v195
	s_nop 1
	v_cndmask_b32_e32 v247, v155, v247, vcc
	v_cmp_le_i32_e32 vcc, v191, v195
	s_nop 1
	v_cndmask_b32_e32 v232, v155, v232, vcc
	v_cmp_le_i32_e32 vcc, v192, v195
	s_nop 1
	v_cndmask_b32_e32 v248, v155, v248, vcc
	v_cmp_le_i32_e32 vcc, v193, v195
	s_nop 1
	v_cndmask_b32_e32 v233, v155, v233, vcc
	v_cmp_le_i32_e32 vcc, v194, v195
	s_nop 1
	v_cndmask_b32_e32 v249, v155, v249, vcc

.Lff1a_bar:
	s_mov_b32 s71, s70
	s_mov_b32 s70, s69
	s_mov_b32 s69, s68
	s_mov_b32 s68, s71
	s_addk_i32 s4, 0x100
	s_add_i32 s26, s26, 64
	s_add_i32 s0, s0, 1
	v_add_u32_e32 v195, 64, v195
	s_add_i32 s27, s0, -2
	s_and_b32 s27, s27, 1
	s_xor_b32 s34, s27, 1
	s_mul_i32 s35, s34, 0x4400
	v_add3_u32 v250, s35, v157, v158
	v_add3_u32 v251, s68, v159, v158
	v_add3_u32 v252, s35, v160, v161
	v_add3_u32 v253, s68, v147, v161
	s_cmp_lt_u32 s0, s1
	s_cselect_b32 s34, s0, s6
	s_sub_i32 s34, s6, s34
	s_lshl_b32 s34, s34, 20
	s_add_u32 s80, s78, s34
	s_addc_u32 s81, s79, 0
	s_add_u32 s80, s80, 0x1000
	s_addc_u32 s81, s81, 0
	s_add_u32 s82, s80, 0x1000
	s_addc_u32 s83, s81, 0
	s_lshr_b32 s77, s7, 2
	s_sub_i32 s77, s77, s26
	s_add_i32 s77, s77, -1
	s_sub_i32 s75, s7, s4
	s_add_i32 s75, s75, -256
	s_lshr_b32 s86, s26, 6
	s_add_i32 s86, s86, -1
	s_lshl_b32 s86, s86, 2
	s_add_i32 s86, s86, 0x1c100
	v_mov_b32_e32 v153, s86
	s_cmp_lg_u32 s7, s4
	s_waitcnt lgkmcnt(0)
	s_barrier
	ds_read_b32 v153, v153
	s_cbranch_scc0 .Lff1a_exit
	s_branch .Lff1b_top2

.Lff1b_top2:
	s_waitcnt vmcnt(3)
	ds_write_b128 v250, v[130:133]
	s_waitcnt vmcnt(2)
	ds_write_b128 v251, v[134:137] offset:34816
	s_waitcnt vmcnt(1)
	ds_write_b128 v252, v[138:141]
	s_waitcnt vmcnt(0)
	ds_write_b128 v253, v[142:145] offset:34816
	global_load_dwordx4 v[130:133], v150, s[80:81]
	global_load_dwordx4 v[134:137], v150, s[82:83]
	global_load_dwordx4 v[138:141], v152, s[80:81]
	global_load_dwordx4 v[142:145], v152, s[82:83]
	s_waitcnt lgkmcnt(4)
	v_readfirstlane_b32 s86, v153
	s_cmpk_eq_u32 s86, 0x200
	s_cbranch_scc1 .Lff1b_exit
	s_cmp_gt_i32 s77, s74
	s_cbranch_scc1 .Lff1b_inact
	s_cmp_eq_u32 s72, 0
	s_cbranch_scc1 .Lff1b_first
	s_mul_i32 s34, s27, 0x4400
	v_add_u32_e32 v0, s34, v162
	ds_read_b128 v[198:201], v0
	ds_read_b128 v[202:205], v0 offset:32
	ds_read_b128 v[206:209], v0 offset:8704
	ds_read_b128 v[210:213], v0 offset:8736
	v_add_u32_e32 v78, s75, v149
	v_add_u32_e32 v66, 0x12800, v78
	v_add_u32_e32 v67, 0x12880, v78
	v_add_u32_e32 v70, 0x12820, v78
	v_add_u32_e32 v71, 0x128a0, v78
	v_add_u32_e32 v74, 0x12840, v78
	v_add_u32_e32 v75, 0x128c0, v78
	v_add_u32_e32 v79, 0x12860, v78
	v_add_u32_e32 v78, 0x128e0, v78
	ds_read_b128 v[82:85], v66
	ds_read_b128 v[66:69], v67
	ds_read_b128 v[86:89], v70
	ds_read_b128 v[70:73], v71
	ds_read_b128 v[90:93], v74
	ds_read_b128 v[74:77], v75
	ds_read_b128 v[94:97], v79
	ds_read_b128 v[78:81], v78
	s_waitcnt lgkmcnt(1)
	v_mfma_f32_32x32x16_bf16 v[82:97], v[198:201], v[98:101], v[82:97]
	v_sub_f32_e32 v218, v218, v197
	v_sub_f32_e32 v219, v219, v197
	v_sub_f32_e32 v220, v220, v197
	v_sub_f32_e32 v221, v221, v197
	v_exp_f32_e32 v218, v218
	v_exp_f32_e32 v219, v219
	v_exp_f32_e32 v220, v220
	v_exp_f32_e32 v221, v221
	s_waitcnt lgkmcnt(0)
	v_mfma_f32_32x32x16_bf16 v[66:81], v[206:209], v[98:101], v[66:81]
	v_sub_f32_e32 v222, v222, v197
	v_sub_f32_e32 v223, v223, v197
	v_sub_f32_e32 v224, v224, v197
	v_sub_f32_e32 v225, v225, v197
	v_exp_f32_e32 v222, v222
	v_exp_f32_e32 v223, v223
	v_exp_f32_e32 v224, v224
	v_exp_f32_e32 v225, v225
	v_mfma_f32_32x32x16_bf16 v[82:97], v[202:205], v[102:105], v[82:97]
	v_sub_f32_e32 v234, v234, v197
	v_sub_f32_e32 v235, v235, v197
	v_sub_f32_e32 v236, v236, v197
	v_sub_f32_e32 v237, v237, v197
	v_exp_f32_e32 v234, v234
	v_exp_f32_e32 v235, v235
	v_exp_f32_e32 v236, v236
	v_exp_f32_e32 v237, v237
	ds_read_b128 v[198:201], v0 offset:64
	ds_read_b128 v[202:205], v0 offset:96
	ds_read_b128 v[206:209], v0 offset:8768
	ds_read_b128 v[214:217], v0 offset:8800
	v_mfma_f32_32x32x16_bf16 v[66:81], v[210:213], v[102:105], v[66:81]
	v_add_f32_e32 v250, v218, v222
	v_add_f32_e32 v251, v219, v223
	v_add_f32_e32 v252, v220, v224
	v_add_f32_e32 v253, v221, v225
	v_sub_f32_e32 v238, v238, v197
	v_sub_f32_e32 v239, v239, v197
	v_sub_f32_e32 v240, v240, v197
	v_sub_f32_e32 v241, v241, v197
	s_waitcnt lgkmcnt(3)
	v_mfma_f32_32x32x16_bf16 v[82:97], v[198:201], v[106:109], v[82:97]
	v_exp_f32_e32 v238, v238
	v_exp_f32_e32 v239, v239
	v_exp_f32_e32 v240, v240
	v_exp_f32_e32 v241, v241
	v_add_f32_e32 v250, v250, v234
	v_add_f32_e32 v251, v251, v235
	v_add_f32_e32 v252, v252, v236
	v_add_f32_e32 v253, v253, v237
	s_waitcnt lgkmcnt(1)
	v_mfma_f32_32x32x16_bf16 v[66:81], v[206:209], v[106:109], v[66:81]
	v_sub_f32_e32 v226, v226, v197
	v_sub_f32_e32 v227, v227, v197
	v_sub_f32_e32 v228, v228, v197
	v_sub_f32_e32 v229, v229, v197
	v_exp_f32_e32 v226, v226
	v_exp_f32_e32 v227, v227
	v_exp_f32_e32 v228, v228
	v_exp_f32_e32 v229, v229
	v_mfma_f32_32x32x16_bf16 v[82:97], v[202:205], v[110:113], v[82:97]
	v_add_f32_e32 v250, v250, v238
	v_add_f32_e32 v251, v251, v239
	v_add_f32_e32 v252, v252, v240
	v_add_f32_e32 v253, v253, v241
	v_sub_f32_e32 v230, v230, v197
	v_sub_f32_e32 v231, v231, v197
	v_sub_f32_e32 v232, v232, v197
	v_sub_f32_e32 v233, v233, v197
	ds_read_b128 v[198:201], v0 offset:128
	ds_read_b128 v[202:205], v0 offset:160
	ds_read_b128 v[206:209], v0 offset:8832
	ds_read_b128 v[210:213], v0 offset:8864
	s_waitcnt lgkmcnt(4)
	v_mfma_f32_32x32x16_bf16 v[66:81], v[214:217], v[110:113], v[66:81]
	v_exp_f32_e32 v230, v230
	v_exp_f32_e32 v231, v231
	v_exp_f32_e32 v232, v232
	v_exp_f32_e32 v233, v233
	v_add_f32_e32 v250, v250, v226
	v_add_f32_e32 v251, v251, v227
	v_add_f32_e32 v252, v252, v228
	v_add_f32_e32 v253, v253, v229
	s_waitcnt lgkmcnt(3)
	v_mfma_f32_32x32x16_bf16 v[82:97], v[198:201], v[114:117], v[82:97]
	v_sub_f32_e32 v242, v242, v197
	v_sub_f32_e32 v243, v243, v197
	v_sub_f32_e32 v244, v244, v197
	v_sub_f32_e32 v245, v245, v197
	v_exp_f32_e32 v242, v242
	v_exp_f32_e32 v243, v243
	v_exp_f32_e32 v244, v244
	v_exp_f32_e32 v245, v245
	s_waitcnt lgkmcnt(1)
	v_mfma_f32_32x32x16_bf16 v[66:81], v[206:209], v[114:117], v[66:81]
	v_add_f32_e32 v250, v250, v230
	v_add_f32_e32 v251, v251, v231
	v_add_f32_e32 v252, v252, v232
	v_add_f32_e32 v253, v253, v233
	v_sub_f32_e32 v246, v246, v197
	v_sub_f32_e32 v247, v247, v197
	v_sub_f32_e32 v248, v248, v197
	v_sub_f32_e32 v249, v249, v197
	v_mfma_f32_32x32x16_bf16 v[82:97], v[202:205], v[118:121], v[82:97]
	v_exp_f32_e32 v246, v246
	v_exp_f32_e32 v247, v247
	v_exp_f32_e32 v248, v248
	v_exp_f32_e32 v249, v249
	v_add_f32_e32 v250, v250, v242
	v_add_f32_e32 v251, v251, v243
	v_add_f32_e32 v252, v252, v244
	v_add_f32_e32 v253, v253, v245
	ds_read_b128 v[198:201], v0 offset:192
	ds_read_b128 v[202:205], v0 offset:224
	ds_read_b128 v[206:209], v0 offset:8896
	ds_read_b128 v[214:217], v0 offset:8928
	s_waitcnt lgkmcnt(4)
	v_mfma_f32_32x32x16_bf16 v[66:81], v[210:213], v[118:121], v[66:81]
	v_add_f32_e32 v250, v250, v246
	v_add_f32_e32 v251, v251, v247
	v_add_f32_e32 v252, v252, v248
	v_add_f32_e32 v253, v253, v249
	v_add_f32_e32 v250, v250, v251
	v_add_f32_e32 v252, v252, v253
	v_add_f32_e32 v250, v250, v252
	v_add_f32_e32 v196, v196, v250
	s_waitcnt lgkmcnt(3)
	v_mfma_f32_32x32x16_bf16 v[82:97], v[198:201], v[122:125], v[82:97]
	v_cvt_pk_bf16_f32 v241, v240, v241
	v_cvt_pk_bf16_f32 v240, v238, v239
	v_cvt_pk_bf16_f32 v239, v236, v237
	v_cvt_pk_bf16_f32 v238, v234, v235
	v_cvt_pk_bf16_f32 v234, v218, v219
	v_cvt_pk_bf16_f32 v235, v220, v221
	v_cvt_pk_bf16_f32 v236, v222, v223
	v_cvt_pk_bf16_f32 v237, v224, v225
	s_waitcnt lgkmcnt(1)
	v_mfma_f32_32x32x16_bf16 v[66:81], v[206:209], v[122:125], v[66:81]
	v_cvt_pk_bf16_f32 v249, v248, v249
	v_cvt_pk_bf16_f32 v248, v246, v247
	v_cvt_pk_bf16_f32 v247, v244, v245
	v_cvt_pk_bf16_f32 v246, v242, v243
	v_cvt_pk_bf16_f32 v242, v226, v227
	v_cvt_pk_bf16_f32 v243, v228, v229
	v_cvt_pk_bf16_f32 v244, v230, v231
	v_cvt_pk_bf16_f32 v245, v232, v233
	v_mfma_f32_32x32x16_bf16 v[82:97], v[202:205], v[126:129], v[82:97]
	s_waitcnt lgkmcnt(0)
	v_mfma_f32_32x32x16_bf16 v[66:81], v[214:217], v[126:129], v[66:81]
	s_add_i32 s76, s77, 63
	s_cmp_le_i32 s76, s5
	s_cbranch_scc1 .Lff1b_z2
	v_cmp_le_i32_e32 vcc, v165, v195
	s_nop 8
	v_cndmask_b32_e32 v66, v155, v66, vcc
	v_cmp_lt_i32_e32 vcc, v163, v195
	s_nop 1
	v_cndmask_b32_e32 v83, v155, v83, vcc
	v_cmp_le_i32_e32 vcc, v163, v195
	s_nop 1
	v_cndmask_b32_e32 v82, v155, v82, vcc
	v_cmp_le_i32_e32 vcc, v166, v195
	s_nop 1
	v_cndmask_b32_e32 v67, v155, v67, vcc
	v_cmp_le_i32_e32 vcc, v167, v195
	s_nop 1
	v_cndmask_b32_e32 v84, v155, v84, vcc
	v_cmp_le_i32_e32 vcc, v168, v195
	s_nop 1
	v_cndmask_b32_e32 v68, v155, v68, vcc
	v_cmp_le_i32_e32 vcc, v169, v195
	s_nop 1
	v_cndmask_b32_e32 v85, v155, v85, vcc
	v_cmp_le_i32_e32 vcc, v170, v195
	s_nop 1
	v_cndmask_b32_e32 v69, v155, v69, vcc
	v_cmp_le_i32_e32 vcc, v171, v195
	s_nop 1
	v_cndmask_b32_e32 v86, v155, v86, vcc
	v_cmp_le_i32_e32 vcc, v172, v195
	s_nop 1
	v_cndmask_b32_e32 v70, v155, v70, vcc
	v_cmp_le_i32_e32 vcc, v173, v195
	s_nop 1
	v_cndmask_b32_e32 v87, v155, v87, vcc
	v_cmp_le_i32_e32 vcc, v174, v195
	s_nop 1
	v_cndmask_b32_e32 v71, v155, v71, vcc
	v_cmp_le_i32_e32 vcc, v175, v195
	s_nop 1
	v_cndmask_b32_e32 v88, v155, v88, vcc
	v_cmp_le_i32_e32 vcc, v176, v195
	s_nop 1
	v_cndmask_b32_e32 v72, v155, v72, vcc
	v_cmp_le_i32_e32 vcc, v177, v195
	s_nop 1
	v_cndmask_b32_e32 v89, v155, v89, vcc
	v_cmp_le_i32_e32 vcc, v178, v195
	s_nop 1
	v_cndmask_b32_e32 v73, v155, v73, vcc
	v_cmp_le_i32_e32 vcc, v179, v195
	s_nop 1
	v_cndmask_b32_e32 v90, v155, v90, vcc
	v_cmp_le_i32_e32 vcc, v180, v195
	s_nop 1
	v_cndmask_b32_e32 v74, v155, v74, vcc
	v_cmp_le_i32_e32 vcc, v181, v195
	s_nop 1
	v_cndmask_b32_e32 v91, v155, v91, vcc
	v_cmp_le_i32_e32 vcc, v182, v195
	s_nop 1
	v_cndmask_b32_e32 v75, v155, v75, vcc
	v_cmp_le_i32_e32 vcc, v183, v195
	s_nop 1
	v_cndmask_b32_e32 v92, v155, v92, vcc
	v_cmp_le_i32_e32 vcc, v184, v195
	s_nop 1
	v_cndmask_b32_e32 v76, v155, v76, vcc
	v_cmp_le_i32_e32 vcc, v185, v195
	s_nop 1
	v_cndmask_b32_e32 v93, v155, v93, vcc
	v_cmp_le_i32_e32 vcc, v186, v195
	s_nop 1
	v_cndmask_b32_e32 v77, v155, v77, vcc
	v_cmp_le_i32_e32 vcc, v187, v195
	s_nop 1
	v_cndmask_b32_e32 v94, v155, v94, vcc
	v_cmp_le_i32_e32 vcc, v188, v195
	s_nop 1
	v_cndmask_b32_e32 v78, v155, v78, vcc
	v_cmp_le_i32_e32 vcc, v189, v195
	s_nop 1
	v_cndmask_b32_e32 v95, v155, v95, vcc
	v_cmp_le_i32_e32 vcc, v190, v195
	s_nop 1
	v_cndmask_b32_e32 v79, v155, v79, vcc
	v_cmp_le_i32_e32 vcc, v191, v195
	s_nop 1
	v_cndmask_b32_e32 v96, v155, v96, vcc
	v_cmp_le_i32_e32 vcc, v192, v195
	s_nop 1
	v_cndmask_b32_e32 v80, v155, v80, vcc
	v_cmp_le_i32_e32 vcc, v193, v195
	s_nop 1
	v_cndmask_b32_e32 v97, v155, v97, vcc
	v_cmp_le_i32_e32 vcc, v194, v195
	s_nop 1
	v_cndmask_b32_e32 v81, v155, v81, vcc
